# attention task epilogues: output stores widened from 8 x 8-byte to 4 x 16-byte per lane (v_permlane32_swap), on top of the gMLP store widening
# speedup vs baseline: 1.0130x; 1.0033x over previous
; __device__ __forceinline__ unsigned pk2(float lo, float hi) { f32x2 v = {lo, hi}; bf16x2_t b = __builtin_convertvector(v, bf16x2_t); return __builtin_bit_cast(unsigned, b); }
; __device__ __forceinline__ void attn_task(const AttnP& P, LAS unsigned char* lds, int b, int hd, int qq, int c, float shift, int lane_in) {
;     ...
;     const size_t tok = (size_t)b * SEQ + c + 16 * (iq0 + q);
;     if (h == 0) P.ssqA[tok * 8 + hd] = ss;
;     bf16_t* orow = P.MIX + tok * DM + hd * 64;
; #pragma unroll
;     for (int e4 = 0; e4 < 4; ++e4) {
;         const int d0 = 8 * e4 + 4 * h;
;         u32x2 w0, w1;
;         w0.x = pk2(o0[4 * e4], o0[4 * e4 + 1]); w0.y = pk2(o0[4 * e4 + 2], o0[4 * e4 + 3]);
;         w1.x = pk2(o1[4 * e4], o1[4 * e4 + 1]); w1.y = pk2(o1[4 * e4 + 2], o1[4 * e4 + 3]);
;         *(u32x2*)(orow + d0) = w0; *(u32x2*)(orow + 32 + d0) = w1;
;     }
.LBB0_168:
	s_or_b64 exec, exec, s[0:1]
	v_readlane_b32 s0, v243, 20
	v_lshlrev_b64 v[34:35], 11, v[190:191]
	v_readlane_b32 s1, v243, 21
	v_lshlrev_b32_e32 v36, 2, v223
	v_ashrrev_i32_e32 v37, 31, v36
	v_lshl_add_u64 v[34:35], s[0:1], 0, v[34:35]
	v_lshl_add_u64 v[34:35], v[34:35], 0, s[58:59]
	v_cvt_pk_bf16_f32 v4, v4, v5
	v_cvt_pk_bf16_f32 v5, v10, v11
	v_cvt_pk_bf16_f32 v2, v2, v3
	v_cvt_pk_bf16_f32 v3, v6, v7
	v_lshl_add_u64 v[6:7], v[36:37], 1, v[34:35]
	v_bfe_u32 v144, v0, 5, 1
	v_lshlrev_b32_e32 v144, 3, v144
	v_mov_b32_e32 v145, 0
	v_lshl_add_u64 v[146:147], v[6:7], 0, v[144:145]
	v_mov_b32_e32 v128, v4
	v_mov_b32_e32 v129, v5
	v_mov_b32_e32 v136, v2
	v_mov_b32_e32 v137, v3
	v_cvt_pk_bf16_f32 v2, v12, v13
	v_cvt_pk_bf16_f32 v3, v16, v17
	v_cvt_pk_bf16_f32 v4, v8, v9
	v_cvt_pk_bf16_f32 v5, v14, v15
	v_mov_b32_e32 v130, v2
	v_mov_b32_e32 v131, v3
	s_nop 1
	v_permlane32_swap_b32_e32 v128, v130
	v_permlane32_swap_b32_e32 v129, v131
	global_store_dwordx4 v[146:147], v[128:131], off
	v_mov_b32_e32 v138, v4
	v_mov_b32_e32 v139, v5
	s_nop 1
	v_permlane32_swap_b32_e32 v136, v138
	v_permlane32_swap_b32_e32 v137, v139
	global_store_dwordx4 v[146:147], v[136:139], off offset:64
	v_cvt_pk_bf16_f32 v2, v20, v21
	v_cvt_pk_bf16_f32 v3, v24, v25
	v_cvt_pk_bf16_f32 v4, v18, v19
	v_cvt_pk_bf16_f32 v5, v22, v23
	s_add_i32 s97, s97, s3
	v_mov_b32_e32 v132, v2
	v_mov_b32_e32 v133, v3
	v_mov_b32_e32 v140, v4
	v_mov_b32_e32 v141, v5
	v_cvt_pk_bf16_f32 v2, v28, v29
	v_cvt_pk_bf16_f32 v3, v32, v33
	v_cvt_pk_bf16_f32 v4, v26, v27
	v_cvt_pk_bf16_f32 v5, v30, v31
	s_cmpk_gt_i32 s97, 0xff
	s_mov_b32 s30, 0x41f00000
	s_movk_i32 s31, 0x90
	s_movk_i32 s36, 0xfec0
	v_mov_b32_e32 v134, v2
	v_mov_b32_e32 v135, v3
	s_nop 1
	v_permlane32_swap_b32_e32 v132, v134
	v_permlane32_swap_b32_e32 v133, v135
	global_store_dwordx4 v[146:147], v[132:135], off offset:32
	v_mov_b32_e32 v142, v4
	v_mov_b32_e32 v143, v5
	s_nop 1
	v_permlane32_swap_b32_e32 v140, v142
	v_permlane32_swap_b32_e32 v141, v143
	global_store_dwordx4 v[146:147], v[140:143], off offset:96
	s_cbranch_scc1 .LBB0_535

; #define LAS __attribute__((address_space(3)))
; __device__ __forceinline__ unsigned pk2(float lo, float hi) { f32x2 v = {lo, hi}; bf16x2_t b = __builtin_convertvector(v, bf16x2_t); return __builtin_bit_cast(unsigned, b); }
; __device__ __forceinline__ int next_tile(int tt, int R0) { while (tt < 26 && !tile_valid(tt, R0)) ++tt; return tt; }
; __device__ __forceinline__ void attn_task(const AttnP& P, LAS unsigned char* lds, int b, int hd, int qq, int c, float shift, int lane_in) {
;     int lane = lane_in; asm volatile("" : "+v"(lane));
;     const int hb = b * 8 + hd, q = lane & 31, h = lane >> 5, R0 = 4 * qq, iq0 = 32 * qq;
;     bf16x8 qf[4];
;     { const bf16_t* qp = P.Q + ((size_t)(hb * 16 + c) * 128 + iq0 + q) * 64 + 8 * h;
; #pragma unroll
;       for (int kk = 0; kk < 4; ++kk) qf[kk] = *(const bf16x8*)(qp + 16 * kk); }
;     bf16x8 gk[4];
;     int gi = next_tile(0, R0);
;     if (gi < 10) attn_load_k(P, lds, hb, gi, c, R0, lane, gk);
;     unsigned long long Hp[2], Hn[2], Bp[2], Bn[2], mT0[2], mT3[2], mAp[2], mAn[2], mLp, mLn;
;     { const LAS unsigned long long* T = (const LAS unsigned long long*)(lds + LDS_ATAB + lane * 144);
;       Hp[0] = T[0]; Hp[1] = T[1]; Hn[0] = T[2]; Hn[1] = T[3]; Bp[0] = T[4]; Bp[1] = T[5]; Bn[0] = T[6]; Bn[1] = T[7];
;       mT0[0] = T[8]; mT0[1] = T[9]; mT3[0] = T[10]; mT3[1] = T[11]; mAp[0] = T[12]; mAp[1] = T[13]; mAn[0] = T[14]; mAn[1] = T[15]; mLp = T[16]; mLn = T[17]; }
;     f32x16 o0 = {}, o1 = {}, zacc = {};
;     bf16x8 ones = {0x3F80, 0x3F80, 0x3F80, 0x3F80, 0x3F80, 0x3F80, 0x3F80, 0x3F80}; asm volatile("" : "+v"(ones));
;     int li = 10, ph = 0;
;     ...
;     const size_t tok = (size_t)b * SEQ + c + 16 * (iq0 + q);
;     if (h == 0) P.ssqA[tok * 8 + hd] = ss;
;     bf16_t* orow = P.MIX + tok * DM + hd * 64;
; #pragma unroll
;     for (int e4 = 0; e4 < 4; ++e4) {
;         const int d0 = 8 * e4 + 4 * h;
;         u32x2 w0, w1;
;         w0.x = pk2(o0[4 * e4], o0[4 * e4 + 1]); w0.y = pk2(o0[4 * e4 + 2], o0[4 * e4 + 3]);
;         w1.x = pk2(o1[4 * e4], o1[4 * e4 + 1]); w1.y = pk2(o1[4 * e4 + 2], o1[4 * e4 + 3]);
;         *(u32x2*)(orow + d0) = w0; *(u32x2*)(orow + 32 + d0) = w1;
;     }
.LBB0_249:
	s_or_b64 exec, exec, s[0:1]
	v_readlane_b32 s0, v243, 20
	v_lshlrev_b64 v[48:49], 11, v[190:191]
	v_readlane_b32 s1, v243, 21
	s_lshl_b32 s58, s98, 7
	v_lshlrev_b32_e32 v52, 2, v17
	v_lshl_add_u64 v[48:49], s[0:1], 0, v[48:49]
	v_lshl_add_u64 v[48:49], v[48:49], 0, s[58:59]
	v_ashrrev_i32_e32 v53, 31, v52
	v_cvt_pk_bf16_f32 v50, v50, v51
	v_cvt_pk_bf16_f32 v51, v34, v35
	v_cvt_pk_bf16_f32 v18, v18, v19
	v_cvt_pk_bf16_f32 v19, v20, v21
	v_lshl_add_u64 v[20:21], v[52:53], 1, v[48:49]
	v_bfe_u32 v144, v0, 5, 1
	v_lshlrev_b32_e32 v144, 3, v144
	v_mov_b32_e32 v145, 0
	v_lshl_add_u64 v[146:147], v[20:21], 0, v[144:145]
	v_mov_b32_e32 v128, v50
	v_mov_b32_e32 v129, v51
	v_mov_b32_e32 v136, v18
	v_mov_b32_e32 v137, v19
	v_cvt_pk_bf16_f32 v18, v36, v37
	v_cvt_pk_bf16_f32 v19, v38, v39
	v_cvt_pk_bf16_f32 v22, v22, v23
	v_cvt_pk_bf16_f32 v23, v24, v25
	v_mov_b32_e32 v130, v18
	v_mov_b32_e32 v131, v19
	s_nop 1
	v_permlane32_swap_b32_e32 v128, v130
	v_permlane32_swap_b32_e32 v129, v131
	global_store_dwordx4 v[146:147], v[128:131], off
	v_mov_b32_e32 v138, v22
	v_mov_b32_e32 v139, v23
	s_nop 1
	v_permlane32_swap_b32_e32 v136, v138
	v_permlane32_swap_b32_e32 v137, v139
	global_store_dwordx4 v[146:147], v[136:139], off offset:64
	v_cvt_pk_bf16_f32 v18, v40, v41
	v_cvt_pk_bf16_f32 v19, v42, v43
	v_cvt_pk_bf16_f32 v22, v26, v27
	v_cvt_pk_bf16_f32 v23, v28, v29
	v_mov_b32_e32 v132, v18
	v_mov_b32_e32 v133, v19
	v_mov_b32_e32 v140, v22
	v_mov_b32_e32 v141, v23
	v_cvt_pk_bf16_f32 v18, v44, v45
	v_cvt_pk_bf16_f32 v19, v46, v47
	v_mov_b32_e32 v229, v201
	s_add_i32 s58, s99, s64
	v_cvt_pk_bf16_f32 v22, v30, v31
	v_cvt_pk_bf16_f32 v23, v32, v33
	v_mov_b32_e32 v134, v18
	v_mov_b32_e32 v135, v19
	s_nop 1
	v_permlane32_swap_b32_e32 v132, v134
	v_permlane32_swap_b32_e32 v133, v135
	global_store_dwordx4 v[146:147], v[132:135], off offset:32
	v_mov_b32_e32 v142, v22
	v_mov_b32_e32 v143, v23
	s_nop 1
	v_permlane32_swap_b32_e32 v140, v142
	v_permlane32_swap_b32_e32 v141, v143
	global_store_dwordx4 v[146:147], v[140:143], off offset:96
	s_lshl_b64 s[26:27], s[58:59], 7
	v_and_b32_e32 v230, 31, v229
	v_ashrrev_i32_e32 v228, 5, v229
	v_or_b32_e32 v17, s26, v230
	v_mov_b32_e32 v19, s27
	v_or_b32_e32 v18, s13, v17
	v_lshlrev_b32_e32 v20, 3, v228
	v_lshlrev_b64 v[18:19], 7, v[18:19]
	v_ashrrev_i32_e32 v21, 31, v20
	v_lshl_add_u64 v[18:19], s[46:47], 0, v[18:19]
	v_lshlrev_b64 v[20:21], 1, v[20:21]
	v_lshl_add_u64 v[18:19], v[18:19], 0, v[20:21]
	global_load_dwordx4 v[86:89], v[18:19], off
	global_load_dwordx4 v[90:93], v[18:19], off offset:32
	global_load_dwordx4 v[94:97], v[18:19], off offset:64
	global_load_dwordx4 v[98:101], v[18:19], off offset:96
	v_lshrrev_b32_e32 v17, 3, v229
	v_bfe_u32 v18, v229, 2, 1
	v_and_or_b32 v22, v17, 2, v18
	v_lshrrev_b32_e32 v17, 1, v229
	v_and_b32_e32 v18, 3, v229
	v_or_b32_e32 v23, s19, v22
	v_and_or_b32 v198, v17, 4, v18
	v_lshl_add_u32 v18, v23, 3, s22
	v_ashrrev_i32_e32 v19, 31, v18
	v_lshl_add_u64 v[18:19], s[26:27], 0, v[18:19]
	v_or_b32_e32 v18, v18, v198
	v_lshlrev_b64 v[18:19], 7, v[18:19]
	v_lshl_add_u64 v[18:19], s[50:51], 0, v[18:19]
	v_lshl_add_u64 v[18:19], v[18:19], 0, v[20:21]
	global_load_dwordx4 v[110:113], v[18:19], off
	global_load_dwordx4 v[126:129], v[18:19], off offset:32
	global_load_dwordx4 v[130:133], v[18:19], off offset:64
	global_load_dwordx4 v[106:109], v[18:19], off offset:96
	v_mul_lo_u32 v17, v229, s31
	v_add_u32_e32 v17, 0, v17
	v_add_u32_e32 v17, 0x24000, v17
	ds_read_b128 v[102:105], v17
	ds_read_b128 v[114:117], v17 offset:16
	ds_read_b128 v[118:121], v17 offset:32
	ds_read_b128 v[122:125], v17 offset:48
	ds_read_b128 v[134:137], v17 offset:64
	ds_read_b128 v[138:141], v17 offset:80
	ds_read_b128 v[142:145], v17 offset:96
	ds_read_b128 v[146:149], v17 offset:112
	ds_read_b128 v[150:153], v17 offset:128
	s_waitcnt lgkmcnt(8)
	v_mad_u64_u32 v[18:19], s[0:1], v102, 3, 0
	v_lshlrev_b32_e32 v24, 3, v22
	v_or_b32_e32 v17, 0xffffffe4, v22
	v_or_b32_e32 v231, s21, v22
	v_mov_b32_e32 v22, v19
	v_or_b32_e32 v232, -16, v23
	v_mad_u64_u32 v[22:23], s[0:1], v103, 3, v[22:23]
	s_waitcnt lgkmcnt(7)
	v_sub_co_u32_e32 v18, vcc, v18, v114
	v_mov_b64_e32 v[156:157], v[84:85]
	s_nop 0
	v_subb_co_u32_e32 v19, vcc, v22, v115, vcc
	s_waitcnt lgkmcnt(5)
	v_lshl_add_u64 v[202:203], v[18:19], 0, v[122:123]
	v_mad_u64_u32 v[18:19], s[0:1], v104, 3, 0
	v_mov_b32_e32 v22, v19
	v_mad_u64_u32 v[22:23], s[0:1], v105, 3, v[22:23]
	v_sub_co_u32_e32 v18, vcc, v18, v116
	v_lshlrev_b32_e32 v190, 4, v230
	s_nop 0
	v_subb_co_u32_e32 v19, vcc, v22, v117, vcc
	v_add_u32_e32 v235, 2, v228
	v_lshl_add_u64 v[204:205], v[18:19], 0, v[124:125]
	v_mov_b32_e32 v18, 0
	s_lshl_b32 s23, s98, 6
	v_mov_b64_e32 v[154:155], v[82:83]
	v_lshl_add_u32 v200, v228, 4, 0
	v_add_u32_e32 v233, s93, v190
	v_add_u32_e32 v234, s21, v228
	v_add_u32_e32 v236, s21, v235
	v_subrev_u32_e32 v237, 26, v228
	s_mov_b32 s19, 10
	v_lshl_add_u32 v238, v228, 10, v214
	v_lshl_add_u64 v[206:207], s[50:51], 0, v[20:21]
	v_lshl_add_u64 v[208:209], s[52:53], 0, v[190:191]
	v_or3_b32 v239, v198, v24, s36
	s_mov_b32 s10, 0
	s_mov_b64 s[0:1], -1
	v_mov_b32_e32 v19, v18
	v_mov_b32_e32 v20, v18
	v_mov_b32_e32 v21, v18
	v_mov_b32_e32 v22, v18
	v_mov_b32_e32 v23, v18
	v_mov_b32_e32 v24, v18
	v_mov_b32_e32 v25, v18
	v_mov_b32_e32 v26, v18
	v_mov_b32_e32 v27, v18
	v_mov_b32_e32 v28, v18
	v_mov_b32_e32 v29, v18
	v_mov_b32_e32 v30, v18
	v_mov_b32_e32 v31, v18
	v_mov_b32_e32 v32, v18
	v_mov_b32_e32 v33, v18
	v_mov_b32_e32 v34, v18
	v_mov_b32_e32 v35, v18
	v_mov_b32_e32 v36, v18
	v_mov_b32_e32 v37, v18
	v_mov_b32_e32 v38, v18
	v_mov_b32_e32 v39, v18
	v_mov_b32_e32 v40, v18
	v_mov_b32_e32 v41, v18
	v_mov_b32_e32 v42, v18
	v_mov_b32_e32 v43, v18
	v_mov_b32_e32 v44, v18
	v_mov_b32_e32 v45, v18
	v_mov_b32_e32 v46, v18
	v_mov_b32_e32 v47, v18
	v_mov_b32_e32 v48, v18
	v_mov_b32_e32 v49, v18
	v_mov_b32_e32 v50, v18
	v_mov_b32_e32 v51, v18
	v_mov_b32_e32 v52, v18
	v_mov_b32_e32 v53, v18
	v_mov_b32_e32 v54, v18
	v_mov_b32_e32 v55, v18
	v_mov_b32_e32 v56, v18
	v_mov_b32_e32 v57, v18
	v_mov_b32_e32 v58, v18
	v_mov_b32_e32 v59, v18
	v_mov_b32_e32 v60, v18
	v_mov_b32_e32 v61, v18
	v_mov_b32_e32 v62, v18
	v_mov_b32_e32 v63, v18
	v_mov_b32_e32 v64, v18
	v_mov_b32_e32 v65, v18
	s_waitcnt vmcnt(4)
	s_branch .LBB0_251

; __device__ __forceinline__ unsigned pk2(float lo, float hi) { f32x2 v = {lo, hi}; bf16x2_t b = __builtin_convertvector(v, bf16x2_t); return __builtin_bit_cast(unsigned, b); }
; __device__ __forceinline__ void attn_task(const AttnP& P, LAS unsigned char* lds, int b, int hd, int qq, int c, float shift, int lane_in) {
;     ...
;     const size_t tok = (size_t)b * SEQ + c + 16 * (iq0 + q);
;     if (h == 0) P.ssqA[tok * 8 + hd] = ss;
;     bf16_t* orow = P.MIX + tok * DM + hd * 64;
; #pragma unroll
;     for (int e4 = 0; e4 < 4; ++e4) {
;         const int d0 = 8 * e4 + 4 * h;
;         u32x2 w0, w1;
;         w0.x = pk2(o0[4 * e4], o0[4 * e4 + 1]); w0.y = pk2(o0[4 * e4 + 2], o0[4 * e4 + 3]);
;         w1.x = pk2(o1[4 * e4], o1[4 * e4 + 1]); w1.y = pk2(o1[4 * e4 + 2], o1[4 * e4 + 3]);
;         *(u32x2*)(orow + d0) = w0; *(u32x2*)(orow + 32 + d0) = w1;
;     }
; __device__ __forceinline__ void attn_unit(const AttnP& P, LAS unsigned char* lds, int b, int hd, int qq, int wave, int lane) {
;     int tid_ = threadIdx.x; asm volatile("" : "+v"(tid_));
;     const int hb = b * 8 + hd, tid = tid_;
;     float shift;
;     { const float mq = wave_max(fabsf(P.gq[lane])), mk = wave_max(fabsf(P.gk[lane])); shift = fminf(8.0f * mq * mk * 1.4426950408889634f, 64.0f); shift = shift > 30.0f ? shift : 0.f; }
;     {
;         u32x4 kr[8], vr[8];
; #pragma unroll
;         for (int j = 0; j < 8; ++j) { const int chunk = tid + 512 * j, row = chunk >> 3, piece = chunk & 7, cls = row >> 5, il = row & 31;
;             kr[j] = *(const u32x4*)(P.K + ((size_t)(hb * 16 + cls) * 128 + 32 * qq + il) * 64 + piece * 8); }
; #pragma unroll
;         for (int j = 0; j < 8; ++j) { const int chunk = tid + 512 * j, cls = chunk >> 8, within = chunk & 255;
;             vr[j] = *(const u32x4*)(P.Vt + ((size_t)(hb * 16 + cls) * 16 + 4 * qq) * 512 + within * 8); }
.LBB0_329:
	s_or_b64 exec, exec, s[0:1]
	v_readlane_b32 s0, v243, 20
	v_lshlrev_b64 v[34:35], 11, v[190:191]
	v_readlane_b32 s1, v243, 21
	s_lshl_b32 s58, s23, 1
	v_lshlrev_b32_e32 v36, 2, v228
	v_lshl_add_u64 v[34:35], s[0:1], 0, v[34:35]
	v_lshl_add_u64 v[34:35], v[34:35], 0, s[58:59]
	v_ashrrev_i32_e32 v37, 31, v36
	v_cvt_pk_bf16_f32 v4, v4, v5
	v_cvt_pk_bf16_f32 v5, v10, v11
	v_cvt_pk_bf16_f32 v2, v2, v3
	v_cvt_pk_bf16_f32 v3, v6, v7
	v_lshl_add_u64 v[6:7], v[36:37], 1, v[34:35]
	v_bfe_u32 v144, v0, 5, 1
	v_lshlrev_b32_e32 v144, 3, v144
	v_mov_b32_e32 v145, 0
	v_lshl_add_u64 v[146:147], v[6:7], 0, v[144:145]
	v_mov_b32_e32 v128, v4
	v_mov_b32_e32 v129, v5
	v_mov_b32_e32 v136, v2
	v_mov_b32_e32 v137, v3
	v_cvt_pk_bf16_f32 v2, v12, v13
	v_cvt_pk_bf16_f32 v3, v16, v17
	v_cvt_pk_bf16_f32 v4, v8, v9
	v_cvt_pk_bf16_f32 v5, v14, v15
	v_mov_b32_e32 v130, v2
	v_mov_b32_e32 v131, v3
	s_nop 1
	v_permlane32_swap_b32_e32 v128, v130
	v_permlane32_swap_b32_e32 v129, v131
	global_store_dwordx4 v[146:147], v[128:131], off
	v_mov_b32_e32 v138, v4
	v_mov_b32_e32 v139, v5
	s_nop 1
	v_permlane32_swap_b32_e32 v136, v138
	v_permlane32_swap_b32_e32 v137, v139
	global_store_dwordx4 v[146:147], v[136:139], off offset:64
	v_cvt_pk_bf16_f32 v2, v20, v21
	v_cvt_pk_bf16_f32 v3, v24, v25
	v_cvt_pk_bf16_f32 v4, v18, v19
	v_cvt_pk_bf16_f32 v5, v22, v23
	v_mov_b32_e32 v132, v2
	v_mov_b32_e32 v133, v3
	v_mov_b32_e32 v140, v4
	v_mov_b32_e32 v141, v5
	v_cvt_pk_bf16_f32 v2, v28, v29
	v_cvt_pk_bf16_f32 v3, v32, v33
	v_mov_b32_e32 v1, v0
	v_cvt_pk_bf16_f32 v4, v26, v27
	v_cvt_pk_bf16_f32 v5, v30, v31
	v_mov_b32_e32 v134, v2
	v_mov_b32_e32 v135, v3
	s_nop 1
	v_permlane32_swap_b32_e32 v132, v134
	v_permlane32_swap_b32_e32 v133, v135
	global_store_dwordx4 v[146:147], v[132:135], off offset:32
	v_mov_b32_e32 v142, v4
	v_mov_b32_e32 v143, v5
	s_nop 1
	v_permlane32_swap_b32_e32 v140, v142
	v_permlane32_swap_b32_e32 v141, v143
	global_store_dwordx4 v[146:147], v[140:143], off offset:96
	s_lshl_b32 s0, s12, 12
	v_add_u32_e32 v70, 0x200, v1
	v_ashrrev_i32_e32 v2, 8, v1
	v_ashrrev_i32_e32 v4, 8, v70
	v_lshlrev_b32_e32 v67, 4, v1
	v_add_u32_e32 v2, s99, v2
	v_add_u32_e32 v4, s99, v4
	v_add_u32_e32 v71, 0x400, v1
	v_add_u32_e32 v72, 0x600, v1
	v_and_b32_e32 v190, 0x70, v67
	v_ashrrev_i32_e32 v3, 31, v2
	v_ashrrev_i32_e32 v5, 31, v4
	v_ashrrev_i32_e32 v10, 8, v71
	v_ashrrev_i32_e32 v12, 8, v72
	v_lshl_add_u64 v[26:27], s[50:51], 0, v[190:191]
	v_lshlrev_b64 v[34:35], 14, v[2:3]
	v_and_b32_e32 v2, 0xf80, v67
	v_lshlrev_b64 v[36:37], 14, v[4:5]
	v_add_u32_e32 v10, s99, v10
	v_add_u32_e32 v12, s99, v12
	v_add_u32_e32 v73, 0x800, v1
	v_add_u32_e32 v74, 0xa00, v1
	v_or_b32_e32 v28, s0, v2
	v_mov_b32_e32 v29, v191
	v_lshl_add_u64 v[2:3], v[26:27], 0, v[34:35]
	v_lshl_add_u64 v[4:5], v[26:27], 0, v[36:37]
	v_ashrrev_i32_e32 v11, 31, v10
	v_ashrrev_i32_e32 v13, 31, v12
	v_ashrrev_i32_e32 v18, 8, v73
	v_ashrrev_i32_e32 v20, 8, v74
	v_lshl_add_u64 v[2:3], v[2:3], 0, v[28:29]
	v_lshl_add_u64 v[6:7], v[4:5], 0, v[28:29]
	v_lshlrev_b64 v[42:43], 14, v[10:11]
	v_lshlrev_b64 v[44:45], 14, v[12:13]
	v_add_u32_e32 v18, s99, v18
	v_add_u32_e32 v20, s99, v20
	v_add_u32_e32 v75, 0xc00, v1
	v_add_u32_e32 v76, 0xe00, v1
	global_load_dwordx4 v[2:5], v[2:3], off
	s_nop 0
	global_load_dwordx4 v[6:9], v[6:7], off
	v_lshl_add_u64 v[10:11], v[26:27], 0, v[42:43]
	v_lshl_add_u64 v[12:13], v[26:27], 0, v[44:45]
	v_ashrrev_i32_e32 v19, 31, v18
	v_ashrrev_i32_e32 v21, 31, v20
	v_ashrrev_i32_e32 v30, 8, v75
	v_ashrrev_i32_e32 v32, 8, v76
	v_lshl_add_u64 v[10:11], v[10:11], 0, v[28:29]
	v_lshl_add_u64 v[14:15], v[12:13], 0, v[28:29]
	v_lshlrev_b64 v[50:51], 14, v[18:19]
	v_lshlrev_b64 v[52:53], 14, v[20:21]
	v_add_u32_e32 v30, s99, v30
	v_add_u32_e32 v32, s99, v32
	global_load_dwordx4 v[10:13], v[10:11], off
	s_nop 0
	global_load_dwordx4 v[14:17], v[14:15], off
	v_lshl_add_u64 v[18:19], v[26:27], 0, v[50:51]
	v_lshl_add_u64 v[20:21], v[26:27], 0, v[52:53]
	v_ashrrev_i32_e32 v31, 31, v30
	v_ashrrev_i32_e32 v33, 31, v32
	v_lshl_add_u64 v[18:19], v[18:19], 0, v[28:29]
	v_lshl_add_u64 v[22:23], v[20:21], 0, v[28:29]
	v_lshlrev_b64 v[58:59], 14, v[30:31]
	v_lshlrev_b64 v[60:61], 14, v[32:33]
	s_add_u32 s0, s52, s0
	global_load_dwordx4 v[18:21], v[18:19], off
	s_nop 0
	global_load_dwordx4 v[22:25], v[22:23], off
	v_lshl_add_u64 v[30:31], v[26:27], 0, v[58:59]
	v_lshl_add_u64 v[26:27], v[26:27], 0, v[60:61]
	s_addc_u32 s1, s53, 0
	v_and_b32_e32 v38, 0xff0, v67
	v_mov_b32_e32 v39, v191
	v_lshl_add_u64 v[30:31], v[30:31], 0, v[28:29]
	v_lshl_add_u64 v[32:33], v[26:27], 0, v[28:29]
	v_lshl_add_u64 v[62:63], s[0:1], 0, v[38:39]
	global_load_dwordx4 v[26:29], v[30:31], off
	s_nop 0
	global_load_dwordx4 v[30:33], v[32:33], off
	v_lshl_add_u64 v[34:35], v[62:63], 0, v[34:35]
	v_lshl_add_u64 v[38:39], v[62:63], 0, v[36:37]
	v_lshl_add_u64 v[42:43], v[62:63], 0, v[42:43]
	v_lshl_add_u64 v[46:47], v[62:63], 0, v[44:45]
	v_lshl_add_u64 v[50:51], v[62:63], 0, v[50:51]
	v_lshl_add_u64 v[54:55], v[62:63], 0, v[52:53]
	global_load_dwordx4 v[34:37], v[34:35], off
	s_nop 0
	global_load_dwordx4 v[38:41], v[38:39], off
	s_nop 0
	global_load_dwordx4 v[42:45], v[42:43], off
	s_nop 0
	global_load_dwordx4 v[46:49], v[46:47], off
	s_nop 0
	global_load_dwordx4 v[50:53], v[50:51], off
	s_nop 0
	global_load_dwordx4 v[54:57], v[54:55], off
	v_lshl_add_u64 v[58:59], v[62:63], 0, v[58:59]
	v_lshl_add_u64 v[62:63], v[62:63], 0, v[60:61]
	global_load_dwordx4 v[58:61], v[58:59], off
	s_nop 0
	global_load_dwordx4 v[62:65], v[62:63], off
	s_nop 0
	global_load_dword v77, v[192:193], off
	global_load_dword v78, v[194:195], off
	v_add_u32_e32 v66, 0, v190
	v_lshrrev_b32_e32 v1, 3, v1
	v_mad_u64_u32 v[68:69], s[0:1], v1, s71, v[66:67]
	v_lshrrev_b32_e32 v1, 3, v70
	s_barrier
; #define LAS __attribute__((address_space(3)))
; __device__ __forceinline__ void attn_unit(const AttnP& P, LAS unsigned char* lds, int b, int hd, int qq, int wave, int lane) {
;     ...
;     { const float mq = wave_max(fabsf(P.gq[lane])), mk = wave_max(fabsf(P.gk[lane])); shift = fminf(8.0f * mq * mk * 1.4426950408889634f, 64.0f); shift = shift > 30.0f ? shift : 0.f; }
;     {
;         u32x4 kr[8], vr[8];
; #pragma unroll
;         for (int j = 0; j < 8; ++j) { const int chunk = tid + 512 * j, row = chunk >> 3, piece = chunk & 7, cls = row >> 5, il = row & 31;
;             kr[j] = *(const u32x4*)(P.K + ((size_t)(hb * 16 + cls) * 128 + 32 * qq + il) * 64 + piece * 8); }
; #pragma unroll
;         for (int j = 0; j < 8; ++j) { const int chunk = tid + 512 * j, cls = chunk >> 8, within = chunk & 255;
;             vr[j] = *(const u32x4*)(P.Vt + ((size_t)(hb * 16 + cls) * 16 + 4 * qq) * 512 + within * 8); }
;         __syncthreads();
; #pragma unroll
;         for (int j = 0; j < 8; ++j) { const int chunk = tid + 512 * j, row = chunk >> 3, piece = chunk & 7;
;             *(LAS u32x4*)(lds + LDS_KC + row * KC_PITCH + piece * 16) = kr[j]; }
; #pragma unroll
;         for (int j = 0; j < 8; ++j) { const int chunk = tid + 512 * j; *(LAS u32x4*)(lds + LDS_VC + chunk * 16) = vr[j]; }
;     }
;     __syncthreads();
	v_mov_b32_e32 v228, v201
	s_lshl_b32 s38, s12, 5
	s_cmp_lg_u32 s12, 0
	s_cselect_b64 s[60:61], -1, 0
	s_cmp_eq_u32 s12, 0
	s_cselect_b64 s[28:29], -1, 0
	s_and_b64 vcc, exec, s[60:61]
	s_waitcnt vmcnt(17)
	ds_write_b128 v68, v[2:5]
	v_mad_u64_u32 v[2:3], s[0:1], v1, s71, v[66:67]
	v_lshrrev_b32_e32 v1, 3, v71
	s_waitcnt vmcnt(16)
	ds_write_b128 v2, v[6:9]
	v_mad_u64_u32 v[2:3], s[0:1], v1, s71, v[66:67]
	v_lshrrev_b32_e32 v1, 3, v72
	s_waitcnt vmcnt(15)
	ds_write_b128 v2, v[10:13]
	v_mad_u64_u32 v[2:3], s[0:1], v1, s71, v[66:67]
	v_lshrrev_b32_e32 v1, 3, v73
	s_waitcnt vmcnt(14)
	ds_write_b128 v2, v[14:17]
	v_mad_u64_u32 v[2:3], s[0:1], v1, s71, v[66:67]
	v_lshrrev_b32_e32 v1, 3, v74
	s_waitcnt vmcnt(13)
	ds_write_b128 v2, v[18:21]
	v_mad_u64_u32 v[2:3], s[0:1], v1, s71, v[66:67]
	v_lshrrev_b32_e32 v1, 3, v75
	s_waitcnt vmcnt(12)
	ds_write_b128 v2, v[22:25]
	v_mad_u64_u32 v[2:3], s[0:1], v1, s71, v[66:67]
	v_lshrrev_b32_e32 v1, 3, v76
	s_waitcnt vmcnt(11)
	ds_write_b128 v2, v[26:29]
	v_mad_u64_u32 v[2:3], s[0:1], v1, s71, v[66:67]
	v_add_u32_e32 v1, 0, v67
	v_add_u32_e32 v1, 0x14000, v1
	s_waitcnt vmcnt(10)
	ds_write_b128 v2, v[30:33]
	s_waitcnt vmcnt(9)
	ds_write_b128 v1, v[34:37]
	s_waitcnt vmcnt(8)
	ds_write_b128 v1, v[38:41] offset:8192
	s_waitcnt vmcnt(7)
	ds_write_b128 v1, v[42:45] offset:16384
	s_waitcnt vmcnt(6)
	ds_write_b128 v1, v[46:49] offset:24576
	s_waitcnt vmcnt(5)
	ds_write_b128 v1, v[50:53] offset:32768
	s_waitcnt vmcnt(4)
	ds_write_b128 v1, v[54:57] offset:40960
	s_waitcnt vmcnt(3)
	ds_write_b128 v1, v[58:61] offset:49152
	s_waitcnt vmcnt(2)
	ds_write_b128 v1, v[62:65] offset:57344
	s_waitcnt lgkmcnt(0)
	s_barrier
	v_mov_b32_e32 v3, s7
	v_and_b32_e32 v229, 31, v228
	v_or_b32_e32 v1, s6, v229
	v_ashrrev_i32_e32 v17, 5, v228
	v_or_b32_e32 v2, s38, v1
	v_lshlrev_b64 v[2:3], 7, v[2:3]
	v_lshlrev_b32_e32 v4, 3, v17
	v_lshl_add_u64 v[2:3], s[46:47], 0, v[2:3]
	v_ashrrev_i32_e32 v5, 31, v4
	v_lshl_add_u64 v[2:3], v[4:5], 1, v[2:3]
	global_load_dwordx4 v[86:89], v[2:3], off
	global_load_dwordx4 v[90:93], v[2:3], off offset:32
	global_load_dwordx4 v[94:97], v[2:3], off offset:64
	global_load_dwordx4 v[98:101], v[2:3], off offset:96
	s_waitcnt vmcnt(5)
	v_and_b32_e32 v1, 0x7fffffff, v77
	ds_bpermute_b32 v1, v225, v1
	s_waitcnt vmcnt(4)
	v_and_b32_e32 v2, 0x7fffffff, v78
	ds_bpermute_b32 v2, v225, v2
	v_max_f32_e64 v3, |v77|, |v77|
	v_max_f32_e64 v6, |v78|, |v78|
	s_waitcnt lgkmcnt(1)
	v_max_f32_e32 v1, v1, v1
	v_max_f32_e32 v1, v3, v1
	s_waitcnt lgkmcnt(0)
	v_max_f32_e32 v2, v2, v2
	ds_bpermute_b32 v3, v224, v1
	v_max_f32_e32 v2, v6, v2
	ds_bpermute_b32 v6, v224, v2
	v_and_b32_e32 v9, 3, v228
	s_mov_b64 s[0:1], -1
	s_waitcnt lgkmcnt(1)
	v_max_f32_e32 v3, v3, v3
	v_max_f32_e32 v1, v1, v3
	s_waitcnt lgkmcnt(0)
	v_max_f32_e32 v6, v6, v6
	ds_bpermute_b32 v3, v223, v1
	v_max_f32_e32 v2, v2, v6
	ds_bpermute_b32 v6, v223, v2
	s_waitcnt lgkmcnt(1)
	v_max_f32_e32 v3, v3, v3
	v_max_f32_e32 v1, v1, v3
	s_waitcnt lgkmcnt(0)
	v_max_f32_e32 v6, v6, v6
	ds_bpermute_b32 v3, v199, v1
	v_max_f32_e32 v2, v2, v6
	ds_bpermute_b32 v6, v199, v2
	s_waitcnt lgkmcnt(1)
	v_max_f32_e32 v3, v3, v3
	v_max_f32_e32 v1, v1, v3
	s_waitcnt lgkmcnt(0)
	v_max_f32_e32 v6, v6, v6
	ds_bpermute_b32 v3, v226, v1
	v_max_f32_e32 v6, v2, v6
	ds_bpermute_b32 v8, v226, v6
	s_waitcnt lgkmcnt(1)
	v_max_f32_e32 v2, v3, v3
	v_max_f32_e32 v2, v1, v2
	s_waitcnt lgkmcnt(0)
	v_max_f32_e32 v1, v8, v8
	v_max_f32_e32 v6, v6, v1
	ds_bpermute_b32 v7, v227, v2
	ds_bpermute_b32 v8, v227, v6
	v_lshrrev_b32_e32 v1, 3, v228
	v_bfe_u32 v3, v228, 2, 1
	v_and_or_b32 v1, v1, 2, v3
	v_lshrrev_b32_e32 v3, 1, v228
	v_and_or_b32 v190, v3, 4, v9
	v_lshlrev_b32_e32 v9, 3, v1
	v_mov_b64_e32 v[198:199], v[190:191]
	s_cbranch_vccnz .LBB0_331
	v_lshlrev_b32_e32 v3, 3, v1
	s_mov_b64 s[0:1], 0
	v_mov_b64_e32 v[198:199], v[190:191]

; __device__ __forceinline__ unsigned pk2(float lo, float hi) { f32x2 v = {lo, hi}; bf16x2_t b = __builtin_convertvector(v, bf16x2_t); return __builtin_bit_cast(unsigned, b); }
; __device__ __forceinline__ int next_tile(int tt, int R0) { while (tt < 26 && !tile_valid(tt, R0)) ++tt; return tt; }
; __device__ __forceinline__ void attn_task(const AttnP& P, LAS unsigned char* lds, int b, int hd, int qq, int c, float shift, int lane_in) {
;     int lane = lane_in; asm volatile("" : "+v"(lane));
;     const int hb = b * 8 + hd, q = lane & 31, h = lane >> 5, R0 = 4 * qq, iq0 = 32 * qq;
;     bf16x8 qf[4];
;     { const bf16_t* qp = P.Q + ((size_t)(hb * 16 + c) * 128 + iq0 + q) * 64 + 8 * h;
; #pragma unroll
;       for (int kk = 0; kk < 4; ++kk) qf[kk] = *(const bf16x8*)(qp + 16 * kk); }
;     bf16x8 gk[4];
;     int gi = next_tile(0, R0);
;     if (gi < 10) attn_load_k(P, lds, hb, gi, c, R0, lane, gk);
;     ...
;     const size_t tok = (size_t)b * SEQ + c + 16 * (iq0 + q);
;     if (h == 0) P.ssqA[tok * 8 + hd] = ss;
;     bf16_t* orow = P.MIX + tok * DM + hd * 64;
; #pragma unroll
;     for (int e4 = 0; e4 < 4; ++e4) {
;         const int d0 = 8 * e4 + 4 * h;
;         u32x2 w0, w1;
;         w0.x = pk2(o0[4 * e4], o0[4 * e4 + 1]); w0.y = pk2(o0[4 * e4 + 2], o0[4 * e4 + 3]);
;         w1.x = pk2(o1[4 * e4], o1[4 * e4 + 1]); w1.y = pk2(o1[4 * e4 + 2], o1[4 * e4 + 3]);
;         *(u32x2*)(orow + d0) = w0; *(u32x2*)(orow + 32 + d0) = w1;
;     }
.LBB0_432:
	s_or_b64 exec, exec, s[0:1]
	v_readlane_b32 s0, v243, 20
	v_lshlrev_b64 v[48:49], 11, v[190:191]
	v_readlane_b32 s1, v243, 21
	v_lshlrev_b32_e32 v52, 2, v17
	v_ashrrev_i32_e32 v53, 31, v52
	v_lshl_add_u64 v[48:49], s[0:1], 0, v[48:49]
	v_lshl_add_u64 v[48:49], v[48:49], 0, s[58:59]
	v_cvt_pk_bf16_f32 v50, v50, v51
	v_cvt_pk_bf16_f32 v51, v34, v35
	v_cvt_pk_bf16_f32 v18, v18, v19
	v_cvt_pk_bf16_f32 v19, v20, v21
	v_lshl_add_u64 v[20:21], v[52:53], 1, v[48:49]
	v_bfe_u32 v144, v0, 5, 1
	v_lshlrev_b32_e32 v144, 3, v144
	v_mov_b32_e32 v145, 0
	v_lshl_add_u64 v[146:147], v[20:21], 0, v[144:145]
	v_mov_b32_e32 v128, v50
	v_mov_b32_e32 v129, v51
	v_mov_b32_e32 v136, v18
	v_mov_b32_e32 v137, v19
	v_cvt_pk_bf16_f32 v18, v36, v37
	v_cvt_pk_bf16_f32 v19, v38, v39
	v_cvt_pk_bf16_f32 v22, v22, v23
	v_cvt_pk_bf16_f32 v23, v24, v25
	v_mov_b32_e32 v130, v18
	v_mov_b32_e32 v131, v19
	s_nop 1
	v_permlane32_swap_b32_e32 v128, v130
	v_permlane32_swap_b32_e32 v129, v131
	global_store_dwordx4 v[146:147], v[128:131], off
	v_mov_b32_e32 v138, v22
	v_mov_b32_e32 v139, v23
	s_nop 1
	v_permlane32_swap_b32_e32 v136, v138
	v_permlane32_swap_b32_e32 v137, v139
	global_store_dwordx4 v[146:147], v[136:139], off offset:64
	v_cvt_pk_bf16_f32 v18, v40, v41
	v_cvt_pk_bf16_f32 v19, v42, v43
	v_cvt_pk_bf16_f32 v22, v26, v27
	v_cvt_pk_bf16_f32 v23, v28, v29
	v_mov_b32_e32 v132, v18
	v_mov_b32_e32 v133, v19
	v_mov_b32_e32 v140, v22
	v_mov_b32_e32 v141, v23
	v_cvt_pk_bf16_f32 v18, v44, v45
	v_cvt_pk_bf16_f32 v19, v46, v47
	v_mov_b32_e32 v224, v201
	v_cvt_pk_bf16_f32 v22, v30, v31
	v_cvt_pk_bf16_f32 v23, v32, v33
	v_mov_b32_e32 v134, v18
	v_mov_b32_e32 v135, v19
	s_nop 1
	v_permlane32_swap_b32_e32 v132, v134
	v_permlane32_swap_b32_e32 v133, v135
	global_store_dwordx4 v[146:147], v[132:135], off offset:32
	v_mov_b32_e32 v142, v22
	v_mov_b32_e32 v143, v23
	s_nop 1
	v_permlane32_swap_b32_e32 v140, v142
	v_permlane32_swap_b32_e32 v141, v143
	global_store_dwordx4 v[146:147], v[140:143], off offset:96
	v_mov_b32_e32 v19, s27
	v_and_b32_e32 v225, 31, v224
	v_or_b32_e32 v17, s26, v225
	v_or_b32_e32 v18, s38, v17
	v_ashrrev_i32_e32 v223, 5, v224
	v_lshlrev_b64 v[18:19], 7, v[18:19]
	v_lshl_add_u64 v[20:21], s[46:47], 0, v[18:19]
	v_lshlrev_b32_e32 v18, 3, v223
	v_ashrrev_i32_e32 v19, 31, v18
	v_lshl_add_u64 v[20:21], v[18:19], 1, v[20:21]
	global_load_dwordx4 v[86:89], v[20:21], off
	global_load_dwordx4 v[90:93], v[20:21], off offset:32
	global_load_dwordx4 v[94:97], v[20:21], off offset:64
	global_load_dwordx4 v[98:101], v[20:21], off offset:96
	v_lshrrev_b32_e32 v17, 3, v224
	v_bfe_u32 v20, v224, 2, 1
	v_and_or_b32 v20, v17, 2, v20
	v_lshrrev_b32_e32 v17, 1, v224
	v_and_b32_e32 v21, 3, v224
	v_and_or_b32 v190, v17, 4, v21
	s_mov_b64 s[0:1], -1
	s_andn2_b64 vcc, exec, s[28:29]
	v_lshlrev_b32_e32 v17, 3, v20
	v_mov_b64_e32 v[198:199], v[190:191]
	s_cbranch_vccnz .LBB0_434
	v_lshlrev_b32_e32 v21, 3, v20
	s_mov_b64 s[0:1], 0
	v_mov_b64_e32 v[198:199], v[190:191]
